# seams P6-P8, P8-P9, P9-P10: barrier among the 4 workgroups that own the same 256-row tile (all dependencies of those seams are inside that group) instead of the 32-workgroup class
# baseline (speedup 1.0000x reference)
.Llb790_go:
	s_and_b32 s0, s74, 63
	s_lshl_b32 s0, s0, 8
	s_add_u32 s0, s0, 0x6000
	s_add_u32 s2, s92, s0
	s_addc_u32 s3, s93, 0
	v_mov_b32_e32 v0, 1
	s_waitcnt vmcnt(0) lgkmcnt(0)
	s_add_u32 s12, s92, 0x5100
	s_addc_u32 s13, s93, 0
	global_load_dword v2, v197, s[12:13] sc1
	global_atomic_add v1, v197, v0, s[2:3] sc0
	buffer_inv sc1
	s_waitcnt vmcnt(0)
	v_readfirstlane_b32 s1, v1
	s_lshr_b32 s8, s1, 2
	s_and_b32 s1, s1, 3
	s_cmp_eq_u32 s1, 3
	s_cbranch_scc1 .Llb790_lead
	s_mov_b32 s9, 0
.Llb790_poll:
	global_load_dword v1, v197, s[2:3] offset:128 sc1
	s_waitcnt vmcnt(0)
	v_readfirstlane_b32 s1, v1
	s_cmp_lg_u32 s1, s8
	s_cbranch_scc1 .Llb790_fin
	s_sleep 1
	s_add_u32 s9, s9, 1
	s_cmp_lt_u32 s9, 0x40000
	s_cbranch_scc1 .Llb790_poll
	s_branch .Llb790_fin
.Llb790_lead:
	global_atomic_add v197, v0, s[2:3] offset:128

.Llb882_go:
	s_and_b32 s0, s74, 63
	s_lshl_b32 s0, s0, 8
	s_add_u32 s0, s0, 0x6000
	s_add_u32 s2, s92, s0
	s_addc_u32 s3, s93, 0
	v_mov_b32_e32 v0, 1
	s_waitcnt vmcnt(0) lgkmcnt(0)
	global_atomic_add v1, v197, v0, s[2:3] sc0
	buffer_inv sc1
	s_waitcnt vmcnt(0)
	v_readfirstlane_b32 s1, v1
	s_lshr_b32 s8, s1, 2
	s_and_b32 s1, s1, 3
	s_cmp_eq_u32 s1, 3
	s_cbranch_scc1 .Llb882_lead
	s_mov_b32 s9, 0
